# RG-LRU chunk totals stored with plain stores (producer and consumer units of a sequence now always share an XCD/L2, no stealing) instead of write-through
# speedup vs baseline: 1.0061x; 1.0061x over previous
.LBB0_1424:
	s_or_b64 exec, exec, s[8:9]
	v_cndmask_b32_e64 v15, v129, v14, s[56:57]
	v_fmac_f32_e32 v157, v158, v17
	s_and_b64 vcc, exec, s[6:7]
	v_fma_f32 v12, v15, v157, v123
	s_cbranch_vccnz .LBB0_1426
	v_add_f32_e32 v11, v116, v12
	s_mov_b32 s53, 0
	s_mov_b64 s[34:35], 0x12800000
	global_store_dword v[26:27], v11, off
	s_branch .LBB0_1427

.LBB0_1427:
	v_cmp_eq_u32_e64 s[8:9], 3, v156
	v_cmp_eq_u32_e32 vcc, s53, v94
	v_mul_f32_e32 v11, v158, v16
	s_lshl_b32 s96, s44, 6
	v_lshl_add_u64 v[158:159], v[58:59], 0, s[34:35]
	s_and_b64 s[34:35], s[8:9], vcc
	v_mul_f32_e32 v15, v15, v11
	v_lshl_add_u64 v[16:17], s[96:97], 3, v[24:25]
	s_and_b64 s[60:61], s[56:57], s[34:35]
	global_store_dword v[158:159], v15, off
	s_and_saveexec_b64 s[34:35], s[60:61]
	s_cbranch_execz .LBB0_1429
	global_store_dword v[16:17], v15, off
	global_store_dword v[16:17], v12, off offset:4
.LBB0_1429:
	s_or_b64 exec, exec, s[34:35]
	v_cndmask_b32_e64 v12, v154, v155, s[56:57]
	v_fma_f32 v15, v12, v157, v117
	s_and_b64 vcc, exec, s[6:7]
	s_mov_b64 s[34:35], 0x11800000
	s_cbranch_vccnz .LBB0_1431
	v_add_f32_e32 v15, v115, v15
	s_mov_b64 s[66:67], 0x12800000
	global_store_dword v[28:29], v15, off
	s_branch .LBB0_1432

.LBB0_1432:
	v_mul_f32_e32 v15, v12, v11
	v_cndmask_b32_e64 v12, v155, v154, s[56:57]
	v_lshl_add_u64 v[154:155], v[60:61], 0, s[66:67]
	global_store_dword v[154:155], v15, off
	s_and_b64 vcc, exec, s[6:7]
	v_fma_f32 v15, v12, v157, v124
	s_cbranch_vccnz .LBB0_1434
	v_add_f32_e32 v15, v113, v15
	s_mov_b64 s[34:35], 0x12800000
	global_store_dword v[30:31], v15, off
	s_branch .LBB0_1435

.LBB0_1435:
	v_mul_f32_e32 v12, v12, v11
	v_cndmask_b32_e64 v14, v14, v131, s[56:57]
	v_lshl_add_u64 v[154:155], v[62:63], 0, s[34:35]
	global_store_dword v[154:155], v12, off
	s_and_b64 vcc, exec, s[6:7]
	v_fma_f32 v12, v14, v157, v125
	s_cbranch_vccnz .LBB0_1437
	v_add_f32_e32 v15, v114, v12
	s_mov_b32 s44, 0
	s_mov_b64 s[34:35], 0x12800000
	global_store_dword v[32:33], v15, off
	s_branch .LBB0_1438

.LBB0_1438:
	v_mul_f32_e32 v11, v14, v11
	v_lshl_add_u64 v[14:15], v[66:67], 0, s[34:35]
	s_xor_b64 s[34:35], s[56:57], -1
	v_cmp_eq_u32_e32 vcc, s44, v94
	s_and_b64 s[60:61], vcc, s[34:35]
	s_and_b64 s[60:61], s[8:9], s[60:61]
	global_store_dword v[14:15], v11, off
	s_and_saveexec_b64 s[66:67], s[60:61]
	s_cbranch_execz .LBB0_1440
	global_store_dword v[16:17], v11, off
	global_store_dword v[16:17], v12, off offset:4

.LBB0_1456:
	s_or_b64 exec, exec, s[66:67]
	v_cndmask_b32_e64 v129, v134, v13, s[56:57]
	v_fmac_f32_e32 v152, v153, v15
	s_and_b64 vcc, exec, s[6:7]
	v_fma_f32 v12, v129, v152, v126
	s_cbranch_vccnz .LBB0_1458
	v_add_f32_e32 v11, v112, v12
	s_mov_b32 s44, 0
	s_mov_b64 s[66:67], 0x12800000
	global_store_dword v[34:35], v11, off
	s_branch .LBB0_1459

.LBB0_1459:
	v_cmp_eq_u32_e32 vcc, s44, v94
	v_mul_f32_e32 v11, v153, v14
	s_and_b64 s[60:61], s[8:9], vcc
	v_mul_f32_e32 v14, v129, v11
	v_lshl_add_u64 v[154:155], v[58:59], 0, s[66:67]
	s_and_b64 s[60:61], s[56:57], s[60:61]
	global_store_dword v[154:155], v14, off offset:64
	s_and_saveexec_b64 s[66:67], s[60:61]
	s_cbranch_execz .LBB0_1461
	global_store_dword v[16:17], v14, off offset:128
	global_store_dword v[16:17], v12, off offset:132
.LBB0_1461:
	s_or_b64 exec, exec, s[66:67]
	v_cndmask_b32_e64 v12, v143, v144, s[56:57]
	v_fma_f32 v14, v12, v152, v118
	s_and_b64 vcc, exec, s[6:7]
	s_mov_b64 s[66:67], 0x11800000
	s_cbranch_vccnz .LBB0_1463
	v_add_f32_e32 v14, v111, v14
	s_mov_b64 vcc, 0x12800000
	global_store_dword v[36:37], v14, off
	s_branch .LBB0_1464

.LBB0_1464:
	v_mul_f32_e32 v129, v12, v11
	v_cndmask_b32_e64 v12, v144, v143, s[56:57]
	v_lshl_add_u64 v[14:15], v[60:61], 0, vcc
	global_store_dword v[14:15], v129, off offset:64
	s_and_b64 vcc, exec, s[6:7]
	v_fma_f32 v14, v12, v152, v127
	s_cbranch_vccnz .LBB0_1466
	v_add_f32_e32 v14, v109, v14
	s_mov_b64 s[66:67], 0x12800000
	global_store_dword v[38:39], v14, off
	s_branch .LBB0_1467

.LBB0_1467:
	v_mul_f32_e32 v12, v12, v11
	v_cndmask_b32_e64 v13, v13, v135, s[56:57]
	v_lshl_add_u64 v[14:15], v[62:63], 0, s[66:67]
	global_store_dword v[14:15], v12, off offset:64
	s_and_b64 vcc, exec, s[6:7]
	v_fma_f32 v12, v13, v152, v128
	s_cbranch_vccnz .LBB0_1469
	v_add_f32_e32 v14, v110, v12
	s_mov_b32 s44, 0
	s_mov_b64 s[66:67], 0x12800000
	global_store_dword v[40:41], v14, off
	s_branch .LBB0_1470

.LBB0_1470:
	v_cmp_eq_u32_e32 vcc, s44, v94
	s_and_b64 s[60:61], vcc, s[34:35]
	v_mul_f32_e32 v11, v13, v11
	v_lshl_add_u64 v[14:15], v[66:67], 0, s[66:67]
	s_and_b64 s[60:61], s[8:9], s[60:61]
	global_store_dword v[14:15], v11, off offset:64
	s_and_saveexec_b64 s[66:67], s[60:61]
	s_cbranch_execz .LBB0_1472
	global_store_dword v[16:17], v11, off offset:128
	global_store_dword v[16:17], v12, off offset:132

.LBB0_1488:
	s_or_b64 exec, exec, s[66:67]
	v_cndmask_b32_e64 v14, v136, v10, s[56:57]
	v_fmac_f32_e32 v20, v21, v13
	s_and_b64 vcc, exec, s[6:7]
	v_fma_f32 v13, v14, v20, v130
	s_cbranch_vccnz .LBB0_1490
	v_add_f32_e32 v11, v108, v13
	s_mov_b32 s44, 0
	s_mov_b64 s[66:67], 0x12800000
	global_store_dword v[42:43], v11, off
	s_branch .LBB0_1491

.LBB0_1491:
	v_cmp_eq_u32_e32 vcc, s44, v94
	v_mul_f32_e32 v11, v21, v12
	s_and_b64 s[60:61], s[8:9], vcc
	v_mul_f32_e32 v12, v14, v11
	v_lshl_add_u64 v[14:15], v[58:59], 0, s[66:67]
	s_and_b64 s[60:61], s[56:57], s[60:61]
	global_store_dword v[14:15], v12, off offset:128
	s_and_saveexec_b64 s[66:67], s[60:61]
	s_cbranch_execz .LBB0_1493
	global_store_dword v[16:17], v12, off offset:256
	global_store_dword v[16:17], v13, off offset:260
.LBB0_1493:
	s_or_b64 exec, exec, s[66:67]
	v_cndmask_b32_e64 v12, v146, v147, s[56:57]
	v_fma_f32 v13, v12, v20, v119
	s_and_b64 vcc, exec, s[6:7]
	s_mov_b64 s[66:67], 0x11800000
	s_cbranch_vccnz .LBB0_1495
	v_add_f32_e32 v13, v107, v13
	s_mov_b64 vcc, 0x12800000
	global_store_dword v[44:45], v13, off
	s_branch .LBB0_1496

.LBB0_1496:
	v_mul_f32_e32 v13, v12, v11
	v_cndmask_b32_e64 v12, v147, v146, s[56:57]
	v_lshl_add_u64 v[14:15], v[60:61], 0, vcc
	global_store_dword v[14:15], v13, off offset:128
	s_and_b64 vcc, exec, s[6:7]
	v_fma_f32 v13, v12, v20, v132
	s_cbranch_vccnz .LBB0_1498
	v_add_f32_e32 v13, v105, v13
	s_mov_b64 s[66:67], 0x12800000
	global_store_dword v[46:47], v13, off
	s_branch .LBB0_1499

.LBB0_1499:
	v_mul_f32_e32 v13, v12, v11
	v_cndmask_b32_e64 v12, v10, v137, s[56:57]
	v_lshl_add_u64 v[14:15], v[62:63], 0, s[66:67]
	s_and_b64 vcc, exec, s[6:7]
	v_fma_f32 v10, v12, v20, v133
	global_store_dword v[14:15], v13, off offset:128
	s_cbranch_vccnz .LBB0_1501
	v_add_f32_e32 v13, v106, v10
	s_mov_b32 s44, 0
	s_mov_b64 s[66:67], 0x12800000
	global_store_dword v[48:49], v13, off
	s_branch .LBB0_1502

.LBB0_1502:
	v_cmp_eq_u32_e32 vcc, s44, v94
	s_and_b64 s[60:61], vcc, s[34:35]
	v_mul_f32_e32 v11, v12, v11
	v_lshl_add_u64 v[12:13], v[66:67], 0, s[66:67]
	s_and_b64 s[60:61], s[8:9], s[60:61]
	global_store_dword v[12:13], v11, off offset:128
	s_and_saveexec_b64 s[66:67], s[60:61]
	s_cbranch_execz .LBB0_1504
	global_store_dword v[16:17], v11, off offset:256
	global_store_dword v[16:17], v10, off offset:260

.LBB0_1520:
	s_or_b64 exec, exec, s[10:11]
	v_cndmask_b32_e64 v12, v138, v9, s[56:57]
	v_fmac_f32_e32 v8, v18, v11
	s_and_b64 vcc, exec, s[6:7]
	v_fma_f32 v11, v12, v8, v122
	s_cbranch_vccnz .LBB0_1522
	v_add_f32_e32 v13, v104, v11
	s_mov_b32 s12, 0
	s_mov_b64 s[10:11], 0x12800000
	global_store_dword v[50:51], v13, off
	s_branch .LBB0_1523

.LBB0_1523:
	v_cmp_eq_u32_e32 vcc, s12, v94
	v_mul_f32_e32 v10, v18, v10
	v_lshl_add_u64 v[14:15], v[58:59], 0, s[10:11]
	s_and_b64 s[10:11], s[8:9], vcc
	v_mul_f32_e32 v12, v12, v10
	s_and_b64 s[12:13], s[56:57], s[10:11]
	global_store_dword v[14:15], v12, off offset:192
	s_and_saveexec_b64 s[10:11], s[12:13]
	s_cbranch_execz .LBB0_1525
	global_store_dword v[16:17], v12, off offset:384
	global_store_dword v[16:17], v11, off offset:388
.LBB0_1525:
	s_or_b64 exec, exec, s[10:11]
	v_cndmask_b32_e64 v11, v141, v142, s[56:57]
	v_fma_f32 v12, v11, v8, v121
	s_and_b64 vcc, exec, s[6:7]
	s_mov_b64 s[10:11], 0x11800000
	s_cbranch_vccnz .LBB0_1527
	v_add_f32_e32 v12, v103, v12
	s_mov_b64 s[12:13], 0x12800000
	global_store_dword v[52:53], v12, off
	s_branch .LBB0_1528

.LBB0_1528:
	v_mul_f32_e32 v14, v11, v10
	v_cndmask_b32_e64 v11, v142, v141, s[56:57]
	v_lshl_add_u64 v[12:13], v[60:61], 0, s[12:13]
	global_store_dword v[12:13], v14, off offset:192
	s_and_b64 vcc, exec, s[6:7]
	v_fma_f32 v12, v11, v8, v140
	s_cbranch_vccnz .LBB0_1530
	v_add_f32_e32 v12, v101, v12
	s_mov_b64 s[10:11], 0x12800000
	global_store_dword v[54:55], v12, off
	s_branch .LBB0_1531

.LBB0_1531:
	v_cndmask_b32_e64 v9, v9, v139, s[56:57]
	v_mul_f32_e32 v11, v11, v10
	v_lshl_add_u64 v[12:13], v[62:63], 0, s[10:11]
	s_and_b64 vcc, exec, s[6:7]
	v_fma_f32 v8, v9, v8, v120
	global_store_dword v[12:13], v11, off offset:192
	s_cbranch_vccnz .LBB0_1533
	v_add_f32_e32 v11, v102, v8
	s_mov_b32 s10, 0
	s_mov_b64 s[6:7], 0x12800000
	global_store_dword v[56:57], v11, off
	s_branch .LBB0_1534

.LBB0_1534:
	v_cmp_eq_u32_e32 vcc, s10, v94
	v_mul_f32_e32 v9, v9, v10
	v_lshl_add_u64 v[10:11], v[66:67], 0, s[6:7]
	s_and_b64 s[6:7], vcc, s[34:35]
	s_and_b64 s[8:9], s[8:9], s[6:7]
	global_store_dword v[10:11], v9, off offset:192
	s_and_saveexec_b64 s[6:7], s[8:9]
	s_cbranch_execz .LBB0_1278
	global_store_dword v[16:17], v9, off offset:384
	global_store_dword v[16:17], v8, off offset:388
	s_branch .LBB0_1278

.LBB0_1705:
	s_or_b64 exec, exec, s[8:9]
	v_cndmask_b32_e64 v15, v129, v14, s[76:77]
	v_fmac_f32_e32 v157, v158, v17
	s_and_b64 vcc, exec, s[6:7]
	v_fma_f32 v12, v15, v157, v123
	s_cbranch_vccnz .LBB0_1707
	v_add_f32_e32 v11, v116, v12
	s_mov_b32 s56, 0
	s_mov_b64 s[34:35], 0x12800000
	global_store_dword v[26:27], v11, off
	s_branch .LBB0_1708

.LBB0_1708:
	v_cmp_eq_u32_e64 s[8:9], 3, v156
	v_cmp_eq_u32_e32 vcc, s56, v94
	v_mul_f32_e32 v11, v158, v16
	s_lshl_b32 s96, s53, 6
	v_lshl_add_u64 v[158:159], v[58:59], 0, s[34:35]
	s_and_b64 s[34:35], s[8:9], vcc
	v_mul_f32_e32 v15, v15, v11
	v_lshl_add_u64 v[16:17], s[96:97], 3, v[24:25]
	s_and_b64 s[56:57], s[76:77], s[34:35]
	global_store_dword v[158:159], v15, off
	s_and_saveexec_b64 s[34:35], s[56:57]
	s_cbranch_execz .LBB0_1710
	global_store_dword v[16:17], v15, off
	global_store_dword v[16:17], v12, off offset:4
.LBB0_1710:
	s_or_b64 exec, exec, s[34:35]
	v_cndmask_b32_e64 v12, v154, v155, s[76:77]
	v_fma_f32 v15, v12, v157, v117
	s_and_b64 vcc, exec, s[6:7]
	s_mov_b64 s[34:35], 0x11800000
	s_cbranch_vccnz .LBB0_1712
	v_add_f32_e32 v15, v115, v15
	s_mov_b64 s[56:57], 0x12800000
	global_store_dword v[28:29], v15, off
	s_branch .LBB0_1713

.LBB0_1713:
	v_mul_f32_e32 v15, v12, v11
	v_cndmask_b32_e64 v12, v155, v154, s[76:77]
	v_lshl_add_u64 v[154:155], v[60:61], 0, s[56:57]
	global_store_dword v[154:155], v15, off
	s_and_b64 vcc, exec, s[6:7]
	v_fma_f32 v15, v12, v157, v124
	s_cbranch_vccnz .LBB0_1715
	v_add_f32_e32 v15, v113, v15
	s_mov_b64 s[34:35], 0x12800000
	global_store_dword v[30:31], v15, off
	s_branch .LBB0_1716

.LBB0_1716:
	v_mul_f32_e32 v12, v12, v11
	v_cndmask_b32_e64 v14, v14, v131, s[76:77]
	v_lshl_add_u64 v[154:155], v[62:63], 0, s[34:35]
	global_store_dword v[154:155], v12, off
	s_and_b64 vcc, exec, s[6:7]
	v_fma_f32 v12, v14, v157, v125
	s_cbranch_vccnz .LBB0_1718
	v_add_f32_e32 v15, v114, v12
	s_mov_b32 s53, 0
	s_mov_b64 s[34:35], 0x12800000
	global_store_dword v[32:33], v15, off
	s_branch .LBB0_1719

.LBB0_1719:
	s_xor_b64 s[56:57], s[76:77], -1
	v_cmp_eq_u32_e32 vcc, s53, v94
	v_mul_f32_e32 v11, v14, v11
	v_lshl_add_u64 v[14:15], v[66:67], 0, s[34:35]
	s_and_b64 s[34:35], vcc, s[56:57]
	s_and_b64 s[60:61], s[8:9], s[34:35]
	global_store_dword v[14:15], v11, off
	s_and_saveexec_b64 s[34:35], s[60:61]
	s_cbranch_execz .LBB0_1721
	global_store_dword v[16:17], v11, off
	global_store_dword v[16:17], v12, off offset:4

.LBB0_1737:
	s_or_b64 exec, exec, s[34:35]
	v_cndmask_b32_e64 v129, v134, v13, s[76:77]
	v_fmac_f32_e32 v152, v153, v15
	s_and_b64 vcc, exec, s[6:7]
	v_fma_f32 v12, v129, v152, v126
	s_cbranch_vccnz .LBB0_1739
	v_add_f32_e32 v11, v112, v12
	s_mov_b32 s53, 0
	s_mov_b64 s[34:35], 0x12800000
	global_store_dword v[34:35], v11, off
	s_branch .LBB0_1740

.LBB0_1740:
	v_cmp_eq_u32_e32 vcc, s53, v94
	v_mul_f32_e32 v11, v153, v14
	v_lshl_add_u64 v[154:155], v[58:59], 0, s[34:35]
	s_and_b64 s[34:35], s[8:9], vcc
	v_mul_f32_e32 v14, v129, v11
	s_and_b64 s[60:61], s[76:77], s[34:35]
	global_store_dword v[154:155], v14, off offset:64
	s_and_saveexec_b64 s[34:35], s[60:61]
	s_cbranch_execz .LBB0_1742
	global_store_dword v[16:17], v14, off offset:128
	global_store_dword v[16:17], v12, off offset:132
.LBB0_1742:
	s_or_b64 exec, exec, s[34:35]
	v_cndmask_b32_e64 v12, v143, v144, s[76:77]
	v_fma_f32 v14, v12, v152, v118
	s_and_b64 vcc, exec, s[6:7]
	s_mov_b64 s[34:35], 0x11800000
	s_cbranch_vccnz .LBB0_1744
	v_add_f32_e32 v14, v111, v14
	s_mov_b64 s[66:67], 0x12800000
	global_store_dword v[36:37], v14, off
	s_branch .LBB0_1745

.LBB0_1745:
	v_mul_f32_e32 v129, v12, v11
	v_cndmask_b32_e64 v12, v144, v143, s[76:77]
	v_lshl_add_u64 v[14:15], v[60:61], 0, s[66:67]
	global_store_dword v[14:15], v129, off offset:64
	s_and_b64 vcc, exec, s[6:7]
	v_fma_f32 v14, v12, v152, v127
	s_cbranch_vccnz .LBB0_1747
	v_add_f32_e32 v14, v109, v14
	s_mov_b64 s[34:35], 0x12800000
	global_store_dword v[38:39], v14, off
	s_branch .LBB0_1748

.LBB0_1748:
	v_mul_f32_e32 v12, v12, v11
	v_cndmask_b32_e64 v13, v13, v135, s[76:77]
	v_lshl_add_u64 v[14:15], v[62:63], 0, s[34:35]
	global_store_dword v[14:15], v12, off offset:64
	s_and_b64 vcc, exec, s[6:7]
	v_fma_f32 v12, v13, v152, v128
	s_cbranch_vccnz .LBB0_1750
	v_add_f32_e32 v14, v110, v12
	s_mov_b32 s53, 0
	s_mov_b64 s[34:35], 0x12800000
	global_store_dword v[40:41], v14, off
	s_branch .LBB0_1751

.LBB0_1751:
	v_cmp_eq_u32_e32 vcc, s53, v94
	v_lshl_add_u64 v[14:15], v[66:67], 0, s[34:35]
	s_and_b64 s[34:35], vcc, s[56:57]
	v_mul_f32_e32 v11, v13, v11
	s_and_b64 s[60:61], s[8:9], s[34:35]
	global_store_dword v[14:15], v11, off offset:64
	s_and_saveexec_b64 s[34:35], s[60:61]
	s_cbranch_execz .LBB0_1753
	global_store_dword v[16:17], v11, off offset:128
	global_store_dword v[16:17], v12, off offset:132

.LBB0_1769:
	s_or_b64 exec, exec, s[34:35]
	v_cndmask_b32_e64 v14, v136, v10, s[76:77]
	v_fmac_f32_e32 v20, v21, v13
	s_and_b64 vcc, exec, s[6:7]
	v_fma_f32 v13, v14, v20, v130
	s_cbranch_vccnz .LBB0_1771
	v_add_f32_e32 v11, v108, v13
	s_mov_b32 s53, 0
	s_mov_b64 s[34:35], 0x12800000
	global_store_dword v[42:43], v11, off
	s_branch .LBB0_1772

.LBB0_1772:
	v_mul_f32_e32 v11, v21, v12
	v_cmp_eq_u32_e32 vcc, s53, v94
	v_mul_f32_e32 v12, v14, v11
	v_lshl_add_u64 v[14:15], v[58:59], 0, s[34:35]
	s_and_b64 s[34:35], s[8:9], vcc
	s_and_b64 s[60:61], s[76:77], s[34:35]
	global_store_dword v[14:15], v12, off offset:128
	s_and_saveexec_b64 s[34:35], s[60:61]
	s_cbranch_execz .LBB0_1774
	global_store_dword v[16:17], v12, off offset:256
	global_store_dword v[16:17], v13, off offset:260
.LBB0_1774:
	s_or_b64 exec, exec, s[34:35]
	v_cndmask_b32_e64 v12, v146, v147, s[76:77]
	v_fma_f32 v13, v12, v20, v119
	s_and_b64 vcc, exec, s[6:7]
	s_mov_b64 s[34:35], 0x11800000
	s_cbranch_vccnz .LBB0_1776
	v_add_f32_e32 v13, v107, v13
	s_mov_b64 s[66:67], 0x12800000
	global_store_dword v[44:45], v13, off
	s_branch .LBB0_1777

.LBB0_1777:
	v_mul_f32_e32 v13, v12, v11
	v_cndmask_b32_e64 v12, v147, v146, s[76:77]
	v_lshl_add_u64 v[14:15], v[60:61], 0, s[66:67]
	global_store_dword v[14:15], v13, off offset:128
	s_and_b64 vcc, exec, s[6:7]
	v_fma_f32 v13, v12, v20, v132
	s_cbranch_vccnz .LBB0_1779
	v_add_f32_e32 v13, v105, v13
	s_mov_b64 s[34:35], 0x12800000
	global_store_dword v[46:47], v13, off
	s_branch .LBB0_1780

.LBB0_1780:
	v_mul_f32_e32 v13, v12, v11
	v_cndmask_b32_e64 v12, v10, v137, s[76:77]
	v_lshl_add_u64 v[14:15], v[62:63], 0, s[34:35]
	s_and_b64 vcc, exec, s[6:7]
	v_fma_f32 v10, v12, v20, v133
	global_store_dword v[14:15], v13, off offset:128
	s_cbranch_vccnz .LBB0_1782
	v_add_f32_e32 v13, v106, v10
	s_mov_b32 s53, 0
	s_mov_b64 s[34:35], 0x12800000
	global_store_dword v[48:49], v13, off
	s_branch .LBB0_1783

.LBB0_1783:
	v_cmp_eq_u32_e32 vcc, s53, v94
	v_mul_f32_e32 v11, v12, v11
	v_lshl_add_u64 v[12:13], v[66:67], 0, s[34:35]
	s_and_b64 s[34:35], vcc, s[56:57]
	s_and_b64 s[60:61], s[8:9], s[34:35]
	global_store_dword v[12:13], v11, off offset:128
	s_and_saveexec_b64 s[34:35], s[60:61]
	s_cbranch_execz .LBB0_1785
	global_store_dword v[16:17], v11, off offset:256
	global_store_dword v[16:17], v10, off offset:260

.LBB0_1801:
	s_or_b64 exec, exec, s[10:11]
	v_cndmask_b32_e64 v12, v138, v9, s[76:77]
	v_fmac_f32_e32 v8, v18, v11
	s_and_b64 vcc, exec, s[6:7]
	v_fma_f32 v11, v12, v8, v122
	s_cbranch_vccnz .LBB0_1803
	v_add_f32_e32 v13, v104, v11
	s_mov_b32 s12, 0
	s_mov_b64 s[10:11], 0x12800000
	global_store_dword v[50:51], v13, off
	s_branch .LBB0_1804

.LBB0_1804:
	v_cmp_eq_u32_e32 vcc, s12, v94
	v_mul_f32_e32 v10, v18, v10
	v_lshl_add_u64 v[14:15], v[58:59], 0, s[10:11]
	s_and_b64 s[10:11], s[8:9], vcc
	v_mul_f32_e32 v12, v12, v10
	s_and_b64 s[12:13], s[76:77], s[10:11]
	global_store_dword v[14:15], v12, off offset:192
	s_and_saveexec_b64 s[10:11], s[12:13]
	s_cbranch_execz .LBB0_1806
	global_store_dword v[16:17], v12, off offset:384
	global_store_dword v[16:17], v11, off offset:388
.LBB0_1806:
	s_or_b64 exec, exec, s[10:11]
	v_cndmask_b32_e64 v11, v141, v142, s[76:77]
	v_fma_f32 v12, v11, v8, v121
	s_and_b64 vcc, exec, s[6:7]
	s_mov_b64 s[10:11], 0x11800000
	s_cbranch_vccnz .LBB0_1808
	v_add_f32_e32 v12, v103, v12
	s_mov_b64 s[12:13], 0x12800000
	global_store_dword v[52:53], v12, off
	s_branch .LBB0_1809

.LBB0_1809:
	v_mul_f32_e32 v14, v11, v10
	v_cndmask_b32_e64 v11, v142, v141, s[76:77]
	v_lshl_add_u64 v[12:13], v[60:61], 0, s[12:13]
	global_store_dword v[12:13], v14, off offset:192
	s_and_b64 vcc, exec, s[6:7]
	v_fma_f32 v12, v11, v8, v140
	s_cbranch_vccnz .LBB0_1811
	v_add_f32_e32 v12, v101, v12
	s_mov_b64 s[10:11], 0x12800000
	global_store_dword v[54:55], v12, off
	s_branch .LBB0_1812

.LBB0_1812:
	v_cndmask_b32_e64 v9, v9, v139, s[76:77]
	v_mul_f32_e32 v11, v11, v10
	v_lshl_add_u64 v[12:13], v[62:63], 0, s[10:11]
	s_and_b64 vcc, exec, s[6:7]
	v_fma_f32 v8, v9, v8, v120
	global_store_dword v[12:13], v11, off offset:192
	s_cbranch_vccnz .LBB0_1814
	v_add_f32_e32 v11, v102, v8
	s_mov_b32 s10, 0
	s_mov_b64 s[6:7], 0x12800000
	global_store_dword v[56:57], v11, off
	s_branch .LBB0_1815

.LBB0_1815:
	v_cmp_eq_u32_e32 vcc, s10, v94
	v_mul_f32_e32 v9, v9, v10
	v_lshl_add_u64 v[10:11], v[66:67], 0, s[6:7]
	s_and_b64 s[6:7], vcc, s[56:57]
	s_and_b64 s[8:9], s[8:9], s[6:7]
	global_store_dword v[10:11], v9, off offset:192
	s_and_saveexec_b64 s[6:7], s[8:9]
	s_cbranch_execz .LBB0_1559
	global_store_dword v[16:17], v9, off offset:384
	global_store_dword v[16:17], v8, off offset:388
	s_branch .LBB0_1559
